# down-projection K-loop: A-fragment LDS read address adds folded into ds_read offsets (4 fewer VALU per iteration)
# baseline (speedup 1.0000x reference)
; #define PG8_STAGE(bufoff, gbase, voff) do { _Pragma("unroll") for (int _i = 0; _i < 2; ++_i) \
;         __builtin_amdgcn_global_load_lds((const unsigned*)((const char*)(gbase) + (voff)[_i]), (PG8_LAS unsigned*)(lds + (bufoff) + ldsw + _i * 8192), 16, 0, 0); } while (0)
; #define PG8_WAIT_V(n) asm volatile("s_waitcnt vmcnt(" #n ")" ::: "memory")
; #define PG8_BAR __builtin_amdgcn_s_barrier()
; template <class Epi, class Sched, bool ALIGN_EPI = false, bool SP2 = false>
; __device__ __forceinline__ void gemm_phase(PG8_LAS unsigned char* lds, const Gemm g, const Sched& S, const Epi& E) {
;     ...
;     for (int i = 0; i < 2; ++i) { int R, C; stage_rc(tid * 16 + i * 8192, R, C); const int Rb = Epi::PERM ? ((R & ~31) + perm32(R & 31)) : R;
;         voffA[i] = (unsigned)(R * K + C) * 2u; voffB[i] = (unsigned)(Rb * K + C) * 2u; }
;     const size_t kstep = (size_t)(BK * 2);
;     const size_t hstep = (size_t)HALF * K * 2;
;     const size_t tstep = 2 * hstep;
;     const unsigned ldsw = (unsigned)wid * 1024u;
;     const int aoff = lds_byte(wr * 64 + fr, fq * 8), boff = lds_byte(wc * 32 + fr, fq * 8);
;     ...
;     Unit cur, nxt; int ui = 0;
;     if (!S.next(0, cur)) return;
;     f32x4 acc[2][2][4][2];
; #pragma unroll
;     for (int a = 0; a < 2; ++a)
; #pragma unroll
;         for (int b = 0; b < 2; ++b)
; #pragma unroll
;             for (int m = 0; m < 4; ++m)
; #pragma unroll
;                 for (int n = 0; n < 2; ++n) acc[a][b][m][n] = (f32x4){0.f, 0.f, 0.f, 0.f};
;     bf16x8 At[4][2], B0[2][2], B1[2][2];
;     const char* cA = (const char*)g.A + (size_t)cur.pm * tstep; const char* cB = (const char*)g.Bt + (size_t)cur.pn * tstep;
;     S.a_ready(cur);
;     if constexpr (SP2) {
;         PG8_STAGE(PG8_SB(0, 0), cB, voffB); PG8_STAGE(PG8_SB(0, 1), cB + hstep, voffB); PG8_STAGE(PG8_SA(0, 0), cA, voffA); PG8_STAGE(PG8_SA(0, 1), cA + hstep, voffA);
;         if (wr == 1) PG8_BAR;
;         PG8_WAIT_V(2); PG8_BAR;
;         PG8_STAGE(PG8_SB(1, 0), cB + kstep, voffB); PG8_STAGE(PG8_SA(1, 0), cA + kstep, voffA); PG8_STAGE(PG8_SB(1, 1), cB + hstep + kstep, voffB);
;         PG8_WAIT_V(6); PG8_BAR;
.LBB0_2226:
	s_add_u32 s14, s14, 0x4800000
	s_addc_u32 s15, s15, 0
	v_lshrrev_b32_e32 v22, 1, v17
	s_add_u32 s47, s16, 0x10a000
	v_and_b32_e32 v22, 24, v22
	s_addc_u32 s48, s17, 0
	v_and_b32_e32 v21, 15, v17
	v_lshlrev_b32_e32 v23, 1, v22
	v_lshlrev_b32_e32 v17, 2, v17
	s_lshl_b32 s4, s4, 5
	v_lshl_or_b32 v1, s22, 6, v21
	v_lshl_or_b32 v21, v21, 6, v23
	s_lshl_b32 s16, s22, 13
	v_and_b32_e32 v17, 32, v17
	s_and_b32 s4, s4, 0x60
	s_add_i32 m0, s18, 0x18000
	v_lshl_add_u64 v[10:11], v[10:11], 0, s[28:29]
	v_bitop3_b32 v23, v21, s16, v17 bitop3:0xde
	s_lshl_b32 s16, s4, 7
	s_waitcnt vmcnt(2)
	s_barrier
	global_load_lds_dwordx4 v[10:11], off
	v_lshl_add_u64 v[8:9], v[8:9], 0, s[28:29]
	s_add_i32 m0, s18, 0x1a000
	s_add_i32 s49, s18, 0x8000
	s_add_i32 s50, s18, 0xa000
	v_bitop3_b32 v198, v21, s16, v17 bitop3:0xde
	v_add_u32_e32 v252, 0x10000, v198
	global_load_lds_dwordx4 v[8:9], off
	v_lshl_add_u64 v[6:7], v[6:7], 0, s[28:29]
	s_mov_b32 m0, s49
	s_add_u32 s16, s24, 0x160080
	global_load_lds_dwordx4 v[6:7], off
	v_lshl_add_u64 v[4:5], v[4:5], 0, s[28:29]
	s_mov_b32 m0, s50
	s_addc_u32 s17, s25, 0
	global_load_lds_dwordx4 v[4:5], off
	s_add_i32 m0, s18, 0x1c000
	s_nop 0
	global_load_lds_dwordx4 v2, s[16:17]
	v_lshl_add_u64 v[4:5], s[16:17], 0, v[180:181]
	s_add_i32 m0, s18, 0x1e000
	s_movk_i32 s22, 0x1600
	global_load_lds_dwordx4 v[4:5], off
	v_or_b32_e32 v199, s4, v22
	v_lshrrev_b32_e32 v5, 1, v16
	v_mul_lo_u32 v4, v19, s22
	s_mov_b32 s4, 0x16000
	v_mad_u64_u32 v[4:5], s[16:17], v5, s4, v[4:5]
	v_or_b32_e32 v4, v4, v18
	v_add_lshl_u32 v4, v4, v20, 1
	v_mov_b32_e32 v5, v3
	s_mov_b64 s[26:27], 0x160080
	v_lshl_add_u64 v[182:183], v[4:5], 0, s[26:27]
	v_lshrrev_b32_e32 v5, 1, v12
	v_mul_lo_u32 v4, v14, s22
	v_mad_u64_u32 v[4:5], s[16:17], v5, s4, v[4:5]
	s_waitcnt vmcnt(6)
	v_or_b32_e32 v4, v4, v13
	v_add_lshl_u32 v4, v4, v15, 1
	v_mov_b32_e32 v5, v3
	s_sext_i32_i8 s54, s23
	s_ashr_i32 s51, s5, 31
	v_lshl_add_u64 v[184:185], v[4:5], 0, s[26:27]
	s_mov_b32 s4, 0
	v_add_u32_e32 v200, 0, v23
	s_barrier

; #define PG8_STAGE(bufoff, gbase, voff) do { _Pragma("unroll") for (int _i = 0; _i < 2; ++_i) \
;         __builtin_amdgcn_global_load_lds((const unsigned*)((const char*)(gbase) + (voff)[_i]), (PG8_LAS unsigned*)(lds + (bufoff) + ldsw + _i * 8192), 16, 0, 0); } while (0)
; #define PG8_LDA(dst, b, h) do { _Pragma("unroll") for (int m = 0; m < 4; ++m) _Pragma("unroll") for (int k = 0; k < 2; ++k) dst[m][k] = *(const PG8_LAS bf16x8*)(lds + PG8_SA(b, h) + aoff + m * 2048 + k * 1024); } while (0)
; #define PG8_LDB(dst, b, h) do { _Pragma("unroll") for (int n = 0; n < 2; ++n) _Pragma("unroll") for (int k = 0; k < 2; ++k) dst[n][k] = *(const PG8_LAS bf16x8*)(lds + PG8_SB(b, h) + boff + n * 2048 + k * 1024); } while (0)
; #define PG8_MMA(ai, bj, At, Bt) do { __builtin_amdgcn_s_setprio(1); _Pragma("unroll") for (int m = 0; m < 4; ++m) _Pragma("unroll") for (int n = 0; n < 2; ++n) _Pragma("unroll") for (int k = 0; k < 2; ++k) \
;         acc[ai][bj][m][n] = __builtin_amdgcn_mfma_f32_16x16x32_bf16(Bt[n][k], At[m][k], acc[ai][bj][m][n], 0, 0, 0); __builtin_amdgcn_s_setprio(0); } while (0)
; #define PG8_WAIT_V(n) asm volatile("s_waitcnt vmcnt(" #n ")" ::: "memory")
; #define PG8_BAR __builtin_amdgcn_s_barrier()
; template <class Epi, class Sched, bool ALIGN_EPI = false, bool SP2 = false>
; __device__ __forceinline__ void gemm_phase(PG8_LAS unsigned char* lds, const Gemm g, const Sched& S, const Epi& E) {
;     ...
;         for (int t = 0; t < nt; t += 2) {
;             const bool last = (t == nt - 2);
;             const char* a1 = cA + (size_t)(t + 1) * kstep;
;             const char* a2 = last ? nA : cA + (size_t)(t + 2) * kstep; const char* b2 = last ? nB : cB + (size_t)(t + 2) * kstep;
;             const char* a3 = a2 + kstep; const char* b3 = b2 + kstep;
;             if (last && has_next) S.a_ready(nxt);
;             if constexpr (SP2) {
;             PG8_LDB(B0, 0, 0); PG8_LDB(B1, 0, 1); PG8_SCHED; PG8_LDA(At, 0, 0); PG8_STAGE(PG8_SA(1, 1), a1 + hstep, voffA);
;             PG8_WAIT_V(8); PG8_WAIT_L(0); PG8_BAR; PG8_MMA(0, 0, At, B0); PG8_MMA(0, 1, At, B1); PG8_BAR; PG8_SCHED;
;             PG8_LDA(At, 0, 1); PG8_STAGE(PG8_SB(0, 0), b2, voffB); PG8_STAGE(PG8_SB(0, 1), b2 + hstep, voffB); PG8_STAGE(PG8_SA(0, 0), a2, voffA);
;             PG8_WAIT_V(8); PG8_WAIT_L(0); PG8_BAR; PG8_MMA(1, 0, At, B0); PG8_MMA(1, 1, At, B1); PG8_BAR; PG8_SCHED;
.LBB0_2238:
	s_add_u32 s24, s20, 0x100
	s_addc_u32 s25, s21, 0
	s_add_i32 s30, 0, 0x10000
	s_cmpk_eq_i32 s42, 0x54
	s_cselect_b32 s37, s17, s25
	s_cselect_b32 s36, s16, s24
	s_cselect_b32 s27, s23, s41
	s_cselect_b32 s26, s22, s40
	s_add_i32 s31, 0, 0x14000
	ds_read_b128 v[124:127], v252
	ds_read_b128 v[128:131], v252 offset:1024
	ds_read_b128 v[132:135], v252 offset:2048
	ds_read_b128 v[136:139], v252 offset:3072
	ds_read_b128 v[148:151], v252 offset:16384
	ds_read_b128 v[152:155], v252 offset:17408
	ds_read_b128 v[156:159], v252 offset:18432
	ds_read_b128 v[160:163], v252 offset:19456
	v_lshl_add_u64 v[210:211], s[20:21], 0, v[184:185]
	s_add_i32 m0, s18, 0xc000
	ds_read_b128 v[164:167], v200
	ds_read_b128 v[168:171], v200 offset:1024
	ds_read_b128 v[172:175], v200 offset:2048
	ds_read_b128 v[186:189], v200 offset:3072
	ds_read_b128 v[190:193], v200 offset:4096
	ds_read_b128 v[194:197], v200 offset:5120
	ds_read_b128 v[202:205], v200 offset:6144
	ds_read_b128 v[206:209], v200 offset:7168
	global_load_lds_dwordx4 v[210:211], off
	v_lshl_add_u64 v[210:211], s[20:21], 0, v[182:183]
	s_add_i32 m0, s18, 0xe000
	s_nop 0
	global_load_lds_dwordx4 v[210:211], off
	s_waitcnt vmcnt(8)
	s_waitcnt lgkmcnt(0)
	s_barrier
	s_setprio 1
	s_waitcnt lgkmcnt(0)
	v_mfma_f32_16x16x32_bf16 v[144:147], v[124:127], v[164:167], v[144:147]
	v_mfma_f32_16x16x32_bf16 v[140:143], v[132:135], v[164:167], v[140:143]
	v_mfma_f32_16x16x32_bf16 v[112:115], v[124:127], v[172:175], v[112:115]
	v_mfma_f32_16x16x32_bf16 v[108:111], v[132:135], v[172:175], v[108:111]
	v_mfma_f32_16x16x32_bf16 v[100:103], v[124:127], v[190:193], v[100:103]
	v_mfma_f32_16x16x32_bf16 v[92:95], v[132:135], v[190:193], v[92:95]
	v_mfma_f32_16x16x32_bf16 v[84:87], v[124:127], v[202:205], v[84:87]
	v_mfma_f32_16x16x32_bf16 v[76:79], v[132:135], v[202:205], v[76:79]
	v_mfma_f32_16x16x32_bf16 v[144:147], v[128:131], v[168:171], v[144:147]
	v_mfma_f32_16x16x32_bf16 v[140:143], v[136:139], v[168:171], v[140:143]
	v_mfma_f32_16x16x32_bf16 v[112:115], v[128:131], v[186:189], v[112:115]
	v_mfma_f32_16x16x32_bf16 v[108:111], v[136:139], v[186:189], v[108:111]
	v_mfma_f32_16x16x32_bf16 v[100:103], v[128:131], v[194:197], v[100:103]
	v_mfma_f32_16x16x32_bf16 v[92:95], v[136:139], v[194:197], v[92:95]
	v_mfma_f32_16x16x32_bf16 v[84:87], v[128:131], v[206:209], v[84:87]
	v_mfma_f32_16x16x32_bf16 v[76:79], v[136:139], v[206:209], v[76:79]
	s_setprio 0
	s_setprio 1
	v_mfma_f32_16x16x32_bf16 v[120:123], v[148:151], v[164:167], v[120:123]
	v_mfma_f32_16x16x32_bf16 v[116:119], v[156:159], v[164:167], v[116:119]
	v_mfma_f32_16x16x32_bf16 v[104:107], v[148:151], v[172:175], v[104:107]
	v_mfma_f32_16x16x32_bf16 v[96:99], v[156:159], v[172:175], v[96:99]
	v_mfma_f32_16x16x32_bf16 v[88:91], v[148:151], v[190:193], v[88:91]
	v_mfma_f32_16x16x32_bf16 v[80:83], v[156:159], v[190:193], v[80:83]
	v_mfma_f32_16x16x32_bf16 v[72:75], v[148:151], v[202:205], v[72:75]
	v_mfma_f32_16x16x32_bf16 v[68:71], v[156:159], v[202:205], v[68:71]
	v_mfma_f32_16x16x32_bf16 v[120:123], v[152:155], v[168:171], v[120:123]
	v_mfma_f32_16x16x32_bf16 v[116:119], v[160:163], v[168:171], v[116:119]
	v_mfma_f32_16x16x32_bf16 v[104:107], v[152:155], v[186:189], v[104:107]
	v_mfma_f32_16x16x32_bf16 v[96:99], v[160:163], v[186:189], v[96:99]
	v_mfma_f32_16x16x32_bf16 v[88:91], v[152:155], v[194:197], v[88:91]
	v_mfma_f32_16x16x32_bf16 v[80:83], v[160:163], v[194:197], v[80:83]
	v_mfma_f32_16x16x32_bf16 v[72:75], v[152:155], v[206:209], v[72:75]
	v_mfma_f32_16x16x32_bf16 v[68:71], v[160:163], v[206:209], v[68:71]
	s_setprio 0
	s_barrier
	s_add_i32 s20, s30, s13
	s_mov_b32 m0, s20
	ds_read_b128 v[164:167], v200 offset:16384
	ds_read_b128 v[168:171], v200 offset:17408
	ds_read_b128 v[172:175], v200 offset:18432
	ds_read_b128 v[186:189], v200 offset:19456
	ds_read_b128 v[190:193], v200 offset:20480
	ds_read_b128 v[194:197], v200 offset:21504
	ds_read_b128 v[202:205], v200 offset:22528
	ds_read_b128 v[206:209], v200 offset:23552
	global_load_lds_dwordx4 v2, s[26:27]
	s_add_i32 m0, s20, 0x2000
	s_add_u32 s20, s26, 0x160000
	s_addc_u32 s21, s27, 0
	s_add_u32 s98, s26, s28
	s_addc_u32 s99, s27, s29
	s_add_u32 s94, s36, s28
	s_addc_u32 s95, s37, s29
	s_add_i32 s30, s31, s13
	global_load_lds_dwordx4 v180, s[26:27]
	s_mov_b32 m0, s30
	s_nop 0
	global_load_lds_dwordx4 v2, s[20:21]
	s_add_i32 m0, s30, 0x2000
	s_nop 0
	global_load_lds_dwordx4 v180, s[20:21]
	s_mov_b32 m0, s18
	s_nop 0
	global_load_lds_dwordx4 v176, s[36:37]
	s_mov_b32 m0, s44
	s_nop 0
	global_load_lds_dwordx4 v178, s[36:37]
	s_waitcnt vmcnt(8)
	s_waitcnt lgkmcnt(0)
	s_barrier
; #define PG8_STAGE(bufoff, gbase, voff) do { _Pragma("unroll") for (int _i = 0; _i < 2; ++_i) \
;         __builtin_amdgcn_global_load_lds((const unsigned*)((const char*)(gbase) + (voff)[_i]), (PG8_LAS unsigned*)(lds + (bufoff) + ldsw + _i * 8192), 16, 0, 0); } while (0)
; #define PG8_LDA(dst, b, h) do { _Pragma("unroll") for (int m = 0; m < 4; ++m) _Pragma("unroll") for (int k = 0; k < 2; ++k) dst[m][k] = *(const PG8_LAS bf16x8*)(lds + PG8_SA(b, h) + aoff + m * 2048 + k * 1024); } while (0)
; #define PG8_LDB(dst, b, h) do { _Pragma("unroll") for (int n = 0; n < 2; ++n) _Pragma("unroll") for (int k = 0; k < 2; ++k) dst[n][k] = *(const PG8_LAS bf16x8*)(lds + PG8_SB(b, h) + boff + n * 2048 + k * 1024); } while (0)
; #define PG8_MMA(ai, bj, At, Bt) do { __builtin_amdgcn_s_setprio(1); _Pragma("unroll") for (int m = 0; m < 4; ++m) _Pragma("unroll") for (int n = 0; n < 2; ++n) _Pragma("unroll") for (int k = 0; k < 2; ++k) \
;         acc[ai][bj][m][n] = __builtin_amdgcn_mfma_f32_16x16x32_bf16(Bt[n][k], At[m][k], acc[ai][bj][m][n], 0, 0, 0); __builtin_amdgcn_s_setprio(0); } while (0)
; #define PG8_WAIT_V(n) asm volatile("s_waitcnt vmcnt(" #n ")" ::: "memory")
; #define PG8_WAIT_L(n) asm volatile("s_waitcnt lgkmcnt(" #n ")" ::: "memory")
; #define PG8_BAR __builtin_amdgcn_s_barrier()
; #define PG8_SCHED __builtin_amdgcn_sched_barrier(0)
; template <class Epi, class Sched, bool ALIGN_EPI = false, bool SP2 = false>
; __device__ __forceinline__ void gemm_phase(PG8_LAS unsigned char* lds, const Gemm g, const Sched& S, const Epi& E) {
;     ...
;             PG8_WAIT_V(8); PG8_WAIT_L(0); PG8_BAR; PG8_MMA(1, 0, At, B0); PG8_MMA(1, 1, At, B1); PG8_BAR; PG8_SCHED;
;             PG8_LDB(B0, 1, 0); PG8_LDB(B1, 1, 1); PG8_SCHED; PG8_LDA(At, 1, 0); PG8_STAGE(PG8_SA(0, 1), a2 + hstep, voffA);
;             PG8_WAIT_V(8); PG8_WAIT_L(0); PG8_BAR; PG8_MMA(0, 0, At, B0); PG8_MMA(0, 1, At, B1); PG8_BAR; PG8_SCHED;
	s_setprio 1
	s_waitcnt lgkmcnt(0)
	v_mfma_f32_16x16x32_bf16 v[64:67], v[124:127], v[164:167], v[64:67]
	v_mfma_f32_16x16x32_bf16 v[60:63], v[132:135], v[164:167], v[60:63]
	v_mfma_f32_16x16x32_bf16 v[52:55], v[124:127], v[172:175], v[52:55]
	v_mfma_f32_16x16x32_bf16 v[44:47], v[132:135], v[172:175], v[44:47]
	v_mfma_f32_16x16x32_bf16 v[36:39], v[124:127], v[190:193], v[36:39]
	v_mfma_f32_16x16x32_bf16 v[28:31], v[132:135], v[190:193], v[28:31]
	v_mfma_f32_16x16x32_bf16 v[20:23], v[124:127], v[202:205], v[20:23]
	v_mfma_f32_16x16x32_bf16 v[12:15], v[132:135], v[202:205], v[12:15]
	v_mfma_f32_16x16x32_bf16 v[64:67], v[128:131], v[168:171], v[64:67]
	v_mfma_f32_16x16x32_bf16 v[60:63], v[136:139], v[168:171], v[60:63]
	v_mfma_f32_16x16x32_bf16 v[52:55], v[128:131], v[186:189], v[52:55]
	v_mfma_f32_16x16x32_bf16 v[44:47], v[136:139], v[186:189], v[44:47]
	v_mfma_f32_16x16x32_bf16 v[36:39], v[128:131], v[194:197], v[36:39]
	v_mfma_f32_16x16x32_bf16 v[28:31], v[136:139], v[194:197], v[28:31]
	v_mfma_f32_16x16x32_bf16 v[20:23], v[128:131], v[206:209], v[20:23]
	v_mfma_f32_16x16x32_bf16 v[12:15], v[136:139], v[206:209], v[12:15]
	s_setprio 0
	s_setprio 1
	v_mfma_f32_16x16x32_bf16 v[56:59], v[148:151], v[164:167], v[56:59]
	v_mfma_f32_16x16x32_bf16 v[48:51], v[156:159], v[164:167], v[48:51]
	v_mfma_f32_16x16x32_bf16 v[40:43], v[148:151], v[172:175], v[40:43]
	v_mfma_f32_16x16x32_bf16 v[32:35], v[156:159], v[172:175], v[32:35]
	v_mfma_f32_16x16x32_bf16 v[24:27], v[148:151], v[190:193], v[24:27]
	v_mfma_f32_16x16x32_bf16 v[16:19], v[156:159], v[190:193], v[16:19]
	v_mfma_f32_16x16x32_bf16 v[8:11], v[148:151], v[202:205], v[8:11]
	v_mfma_f32_16x16x32_bf16 v[4:7], v[156:159], v[202:205], v[4:7]
	v_mfma_f32_16x16x32_bf16 v[56:59], v[152:155], v[168:171], v[56:59]
	v_mfma_f32_16x16x32_bf16 v[48:51], v[160:163], v[168:171], v[48:51]
	v_mfma_f32_16x16x32_bf16 v[40:43], v[152:155], v[186:189], v[40:43]
	v_mfma_f32_16x16x32_bf16 v[32:35], v[160:163], v[186:189], v[32:35]
	v_mfma_f32_16x16x32_bf16 v[24:27], v[152:155], v[194:197], v[24:27]
	v_mfma_f32_16x16x32_bf16 v[16:19], v[160:163], v[194:197], v[16:19]
	v_mfma_f32_16x16x32_bf16 v[8:11], v[152:155], v[206:209], v[8:11]
	v_mfma_f32_16x16x32_bf16 v[4:7], v[160:163], v[206:209], v[4:7]
	s_setprio 0
	s_barrier
	s_add_i32 s30, 0, 0x18000
	s_add_i32 s31, 0, 0x1c000
	ds_read_b128 v[124:127], v252 offset:32768
	ds_read_b128 v[128:131], v252 offset:33792
	ds_read_b128 v[132:135], v252 offset:34816
	ds_read_b128 v[136:139], v252 offset:35840
	ds_read_b128 v[148:151], v252 offset:49152
	ds_read_b128 v[152:155], v252 offset:50176
	ds_read_b128 v[156:159], v252 offset:51200
	ds_read_b128 v[160:163], v252 offset:52224
	s_add_u32 s20, s36, 0x160000
	s_addc_u32 s21, s37, 0
	s_mov_b32 m0, s45
	ds_read_b128 v[164:167], v200 offset:32768
	ds_read_b128 v[168:171], v200 offset:33792
	ds_read_b128 v[172:175], v200 offset:34816
	ds_read_b128 v[186:189], v200 offset:35840
	ds_read_b128 v[190:193], v200 offset:36864
	ds_read_b128 v[194:197], v200 offset:37888
	ds_read_b128 v[202:205], v200 offset:38912
	ds_read_b128 v[206:209], v200 offset:39936
	global_load_lds_dwordx4 v176, s[20:21]
	s_mov_b32 m0, s46
	s_nop 0
	global_load_lds_dwordx4 v178, s[20:21]
	s_waitcnt vmcnt(8)
	s_waitcnt lgkmcnt(0)
	s_barrier
	s_setprio 1
	s_waitcnt lgkmcnt(0)
	v_mfma_f32_16x16x32_bf16 v[144:147], v[124:127], v[164:167], v[144:147]
	v_mfma_f32_16x16x32_bf16 v[140:143], v[132:135], v[164:167], v[140:143]
	v_mfma_f32_16x16x32_bf16 v[112:115], v[124:127], v[172:175], v[112:115]
	v_mfma_f32_16x16x32_bf16 v[108:111], v[132:135], v[172:175], v[108:111]
	v_mfma_f32_16x16x32_bf16 v[100:103], v[124:127], v[190:193], v[100:103]
	v_mfma_f32_16x16x32_bf16 v[92:95], v[132:135], v[190:193], v[92:95]
	v_mfma_f32_16x16x32_bf16 v[84:87], v[124:127], v[202:205], v[84:87]
	v_mfma_f32_16x16x32_bf16 v[76:79], v[132:135], v[202:205], v[76:79]
	v_mfma_f32_16x16x32_bf16 v[144:147], v[128:131], v[168:171], v[144:147]
	v_mfma_f32_16x16x32_bf16 v[140:143], v[136:139], v[168:171], v[140:143]
	v_mfma_f32_16x16x32_bf16 v[112:115], v[128:131], v[186:189], v[112:115]
	v_mfma_f32_16x16x32_bf16 v[108:111], v[136:139], v[186:189], v[108:111]
	v_mfma_f32_16x16x32_bf16 v[100:103], v[128:131], v[194:197], v[100:103]
	v_mfma_f32_16x16x32_bf16 v[92:95], v[136:139], v[194:197], v[92:95]
	v_mfma_f32_16x16x32_bf16 v[84:87], v[128:131], v[206:209], v[84:87]
	v_mfma_f32_16x16x32_bf16 v[76:79], v[136:139], v[206:209], v[76:79]
	s_setprio 0
	s_setprio 1
	v_mfma_f32_16x16x32_bf16 v[120:123], v[148:151], v[164:167], v[120:123]
	v_mfma_f32_16x16x32_bf16 v[116:119], v[156:159], v[164:167], v[116:119]
	v_mfma_f32_16x16x32_bf16 v[104:107], v[148:151], v[172:175], v[104:107]
	v_mfma_f32_16x16x32_bf16 v[96:99], v[156:159], v[172:175], v[96:99]
	v_mfma_f32_16x16x32_bf16 v[88:91], v[148:151], v[190:193], v[88:91]
	v_mfma_f32_16x16x32_bf16 v[80:83], v[156:159], v[190:193], v[80:83]
	v_mfma_f32_16x16x32_bf16 v[72:75], v[148:151], v[202:205], v[72:75]
	v_mfma_f32_16x16x32_bf16 v[68:71], v[156:159], v[202:205], v[68:71]
	v_mfma_f32_16x16x32_bf16 v[120:123], v[152:155], v[168:171], v[120:123]
	v_mfma_f32_16x16x32_bf16 v[116:119], v[160:163], v[168:171], v[116:119]
	v_mfma_f32_16x16x32_bf16 v[104:107], v[152:155], v[186:189], v[104:107]
	v_mfma_f32_16x16x32_bf16 v[96:99], v[160:163], v[186:189], v[96:99]
	v_mfma_f32_16x16x32_bf16 v[88:91], v[152:155], v[194:197], v[88:91]
	v_mfma_f32_16x16x32_bf16 v[80:83], v[160:163], v[194:197], v[80:83]
	v_mfma_f32_16x16x32_bf16 v[72:75], v[152:155], v[206:209], v[72:75]
	v_mfma_f32_16x16x32_bf16 v[68:71], v[160:163], v[206:209], v[68:71]
	s_setprio 0
	s_barrier
;     __device__ __forceinline__ void operator()(const f32x4 (&acc)[2][2][4][2], const Unit& u, int wr, int wc, int fr, int fq) const {
;         const int row0 = u.pm * BM + wr * 64 + fr; const int col0 = u.pn * BM + wc * 32 + 8 * fq;
;         const float* gp = gate + (size_t)((u.pm * BM) >> 12) * gstride + col0;
;         f32x4 gv[2][2];
; #pragma unroll
;         for (int bj = 0; bj < 2; ++bj)
; #pragma unroll
;             for (int n = 0; n < 2; ++n) gv[bj][n] = *(const f32x4*)(gp + bj * HALF + n * 4);
;         if (base_f32) { const float* bp = (const float*)base;
; #pragma unroll
;             for (int ai = 0; ai < 2; ++ai)
; #pragma unroll
;                 for (int m2 = 0; m2 < 2; ++m2) { f32x4 bs[2][2][2];
; #pragma unroll
;                     for (int mm = 0; mm < 2; ++mm) { const size_t off = (size_t)(row0 + ai * HALF + (2 * m2 + mm) * 16) * ldc + col0;
; #pragma unroll
;                         for (int bj = 0; bj < 2; ++bj)
; #pragma unroll
;                             for (int n = 0; n < 2; ++n) bs[mm][bj][n] = *(const f32x4*)(bp + off + bj * HALF + n * 4); }
; #pragma unroll
;                     for (int mm = 0; mm < 2; ++mm) { const size_t off = (size_t)(row0 + ai * HALF + (2 * m2 + mm) * 16) * ldc + col0;
; #pragma unroll
;                         for (int bj = 0; bj < 2; ++bj) { const f32x4 v0 = bs[mm][bj][0] + gv[bj][0] * acc[ai][bj][2 * m2 + mm][0], v1 = bs[mm][bj][1] + gv[bj][1] * acc[ai][bj][2 * m2 + mm][1];
;                             u32x4 w; w.x = cvt_pk_bf16(v0[0], v0[1]); w.y = cvt_pk_bf16(v0[2], v0[3]); w.z = cvt_pk_bf16(v1[0], v1[1]); w.w = cvt_pk_bf16(v1[2], v1[3]);
;                             *(u32x4*)(out + off + bj * HALF) = w; } }
;                     asm volatile("" ::: "memory"); }
;         } else { const bf16_t* bp = (const bf16_t*)base;
; #pragma unroll
;             for (int ai = 0; ai < 2; ++ai) { u32x4 bs[4][2];
; #pragma unroll
; template <class Epi, class Sched, bool ALIGN_EPI = false, bool SP2 = false>
; __device__ __forceinline__ void gemm_phase(PG8_LAS unsigned char* lds, const Gemm g, const Sched& S, const Epi& E) {
;     ...
;             PG8_LDA(At, 1, 1); PG8_STAGE(PG8_SB(1, 0), b3, voffB); PG8_STAGE(PG8_SB(1, 1), b3 + hstep, voffB); PG8_STAGE(PG8_SA(1, 0), a3, voffA);
;             PG8_WAIT_V(8); PG8_WAIT_L(0); PG8_BAR; PG8_MMA(1, 0, At, B0); PG8_MMA(1, 1, At, B1); PG8_BAR; PG8_SCHED;
	s_add_i32 s20, s30, s13
	s_mov_b32 m0, s20
	ds_read_b128 v[164:167], v200 offset:49152
	ds_read_b128 v[168:171], v200 offset:50176
	ds_read_b128 v[172:175], v200 offset:51200
	ds_read_b128 v[186:189], v200 offset:52224
	ds_read_b128 v[190:193], v200 offset:53248
	ds_read_b128 v[194:197], v200 offset:54272
	ds_read_b128 v[202:205], v200 offset:55296
	ds_read_b128 v[206:209], v200 offset:56320
	global_load_lds_dwordx4 v2, s[98:99]
	s_add_i32 m0, s20, 0x2000
	s_add_u32 s20, s26, 0x160080
	s_addc_u32 s21, s27, 0
	s_add_i32 s26, s31, s13
	global_load_lds_dwordx4 v180, s[98:99]
	s_mov_b32 m0, s26
	s_nop 0
	global_load_lds_dwordx4 v2, s[20:21]
	s_add_i32 m0, s26, 0x2000
	s_nop 0
	global_load_lds_dwordx4 v180, s[20:21]
	s_mov_b32 m0, s49
	s_nop 0
	global_load_lds_dwordx4 v176, s[94:95]
	s_mov_b32 m0, s50
	s_nop 0
	global_load_lds_dwordx4 v178, s[94:95]
	s_waitcnt vmcnt(8)
	s_waitcnt lgkmcnt(0)
	s_barrier
	s_setprio 1
	s_waitcnt lgkmcnt(0)
	v_mfma_f32_16x16x32_bf16 v[64:67], v[124:127], v[164:167], v[64:67]
	v_mfma_f32_16x16x32_bf16 v[60:63], v[132:135], v[164:167], v[60:63]
	v_mfma_f32_16x16x32_bf16 v[52:55], v[124:127], v[172:175], v[52:55]
	v_mfma_f32_16x16x32_bf16 v[44:47], v[132:135], v[172:175], v[44:47]
	v_mfma_f32_16x16x32_bf16 v[36:39], v[124:127], v[190:193], v[36:39]
	v_mfma_f32_16x16x32_bf16 v[28:31], v[132:135], v[190:193], v[28:31]
	v_mfma_f32_16x16x32_bf16 v[20:23], v[124:127], v[202:205], v[20:23]
	v_mfma_f32_16x16x32_bf16 v[12:15], v[132:135], v[202:205], v[12:15]
	v_mfma_f32_16x16x32_bf16 v[64:67], v[128:131], v[168:171], v[64:67]
	v_mfma_f32_16x16x32_bf16 v[60:63], v[136:139], v[168:171], v[60:63]
	v_mfma_f32_16x16x32_bf16 v[52:55], v[128:131], v[186:189], v[52:55]
	v_mfma_f32_16x16x32_bf16 v[44:47], v[136:139], v[186:189], v[44:47]
	v_mfma_f32_16x16x32_bf16 v[36:39], v[128:131], v[194:197], v[36:39]
	v_mfma_f32_16x16x32_bf16 v[28:31], v[136:139], v[194:197], v[28:31]
	v_mfma_f32_16x16x32_bf16 v[20:23], v[128:131], v[206:209], v[20:23]
	v_mfma_f32_16x16x32_bf16 v[12:15], v[136:139], v[206:209], v[12:15]
	s_setprio 0
	s_setprio 1
	v_mfma_f32_16x16x32_bf16 v[56:59], v[148:151], v[164:167], v[56:59]
	v_mfma_f32_16x16x32_bf16 v[48:51], v[156:159], v[164:167], v[48:51]
	v_mfma_f32_16x16x32_bf16 v[40:43], v[148:151], v[172:175], v[40:43]
	v_mfma_f32_16x16x32_bf16 v[32:35], v[156:159], v[172:175], v[32:35]
	v_mfma_f32_16x16x32_bf16 v[24:27], v[148:151], v[190:193], v[24:27]
	v_mfma_f32_16x16x32_bf16 v[16:19], v[156:159], v[190:193], v[16:19]
	v_mfma_f32_16x16x32_bf16 v[8:11], v[148:151], v[202:205], v[8:11]
	v_mfma_f32_16x16x32_bf16 v[4:7], v[156:159], v[202:205], v[4:7]
	v_mfma_f32_16x16x32_bf16 v[56:59], v[152:155], v[168:171], v[56:59]
	v_mfma_f32_16x16x32_bf16 v[48:51], v[160:163], v[168:171], v[48:51]
	v_mfma_f32_16x16x32_bf16 v[40:43], v[152:155], v[186:189], v[40:43]
	v_mfma_f32_16x16x32_bf16 v[32:35], v[160:163], v[186:189], v[32:35]
	v_mfma_f32_16x16x32_bf16 v[24:27], v[152:155], v[194:197], v[24:27]
	v_mfma_f32_16x16x32_bf16 v[16:19], v[160:163], v[194:197], v[16:19]
	v_mfma_f32_16x16x32_bf16 v[8:11], v[152:155], v[206:209], v[8:11]
	v_mfma_f32_16x16x32_bf16 v[4:7], v[160:163], v[206:209], v[4:7]
	s_setprio 0
	s_barrier
	s_add_i32 s42, s42, 2
	s_add_u32 s40, s40, 0x100
	s_addc_u32 s41, s41, 0
	s_cmpk_gt_u32 s42, 0x55
	s_mov_b64 s[20:21], s[24:25]
	s_cbranch_scc0 .LBB0_2238
	v_lshl_or_b32 v148, s54, 8, v199
	s_ashr_i32 s20, s33, 4
	s_mul_hi_i32 s21, s20, 0xc000
	s_mul_i32 s20, s20, 0xc000
	v_ashrrev_i32_e32 v149, 31, v148
	v_lshl_add_u32 v150, s33, 8, v1
	s_add_u32 s20, s47, s20
	v_ashrrev_i32_e32 v151, 31, v150
	v_lshlrev_b64 v[186:187], 1, v[148:149]
	s_addc_u32 s21, s48, s21
	v_lshl_add_u64 v[188:189], s[14:15], 0, v[186:187]
	v_lshlrev_b64 v[190:191], 12, v[150:151]
	v_lshl_add_u64 v[124:125], v[148:149], 2, s[20:21]
	v_lshl_add_u64 v[148:149], v[188:189], 0, v[190:191]
	flat_load_dwordx4 v[136:139], v[124:125]
	flat_load_dwordx4 v[132:135], v[124:125] offset:16
	flat_load_dwordx4 v[128:131], v[124:125] offset:512
	s_nop 0
	flat_load_dwordx4 v[124:127], v[124:125] offset:528
	s_nop 0
	flat_load_dwordx4 v[202:205], v[148:149]
	flat_load_dwordx4 v[172:175], v[148:149] offset:256
	v_or_b32_e32 v148, 16, v150
	v_ashrrev_i32_e32 v149, 31, v148
	v_lshlrev_b64 v[196:197], 12, v[148:149]
	v_lshl_add_u64 v[148:149], v[188:189], 0, v[196:197]
	flat_load_dwordx4 v[168:171], v[148:149]
	flat_load_dwordx4 v[164:167], v[148:149] offset:256
	v_or_b32_e32 v148, 32, v150
	v_ashrrev_i32_e32 v149, 31, v148
	v_lshlrev_b64 v[194:195], 12, v[148:149]
	v_lshl_add_u64 v[148:149], v[188:189], 0, v[194:195]
	flat_load_dwordx4 v[160:163], v[148:149]
	flat_load_dwordx4 v[152:155], v[148:149] offset:256
	v_or_b32_e32 v148, 48, v150
	v_ashrrev_i32_e32 v149, 31, v148
	v_lshlrev_b64 v[192:193], 12, v[148:149]
	v_lshl_add_u64 v[148:149], v[188:189], 0, v[192:193]
	flat_load_dwordx4 v[156:159], v[148:149]
	s_nop 0
	flat_load_dwordx4 v[148:151], v[148:149] offset:256
	s_mov_b64 s[20:21], 0x80000
	s_and_b64 vcc, exec, s[38:39]
	s_mov_b32 s54, s52
	s_mov_b32 s33, s53
	s_mov_b64 s[24:25], s[22:23]
	s_waitcnt vmcnt(0) lgkmcnt(0)
; __device__ __forceinline__ unsigned cvt_pk_bf16(float lo, float hi) { unsigned r; asm volatile("v_cvt_pk_bf16_f32 %0, %1, %2" : "=v"(r) : "v"(lo), "v"(hi)); return r; }
;     __device__ __forceinline__ void operator()(const f32x4 (&acc)[2][2][4][2], const Unit& u, int wr, int wc, int fr, int fq) const {
;     ...
;                 for (int m = 0; m < 4; ++m) { const size_t off = (size_t)(row0 + ai * HALF + m * 16) * ldc + col0;
; #pragma unroll
;                     for (int bj = 0; bj < 2; ++bj) { const u32x4 r = bs[m][bj]; const f32x4 a0 = acc[ai][bj][m][0], a1 = acc[ai][bj][m][1];
;                         u32x4 w;
;                         w.x = cvt_pk_bf16(__builtin_bit_cast(float, r.x << 16) + gv[bj][0][0] * a0[0], __builtin_bit_cast(float, r.x & 0xffff0000u) + gv[bj][0][1] * a0[1]);
;                         w.y = cvt_pk_bf16(__builtin_bit_cast(float, r.y << 16) + gv[bj][0][2] * a0[2], __builtin_bit_cast(float, r.y & 0xffff0000u) + gv[bj][0][3] * a0[3]);
;                         w.z = cvt_pk_bf16(__builtin_bit_cast(float, r.z << 16) + gv[bj][1][0] * a1[0], __builtin_bit_cast(float, r.z & 0xffff0000u) + gv[bj][1][1] * a1[1]);
;                         w.w = cvt_pk_bf16(__builtin_bit_cast(float, r.w << 16) + gv[bj][1][2] * a1[2], __builtin_bit_cast(float, r.w & 0xffff0000u) + gv[bj][1][3] * a1[3]);
;                         *(u32x4*)(out + off + bj * HALF) = w; } }
	v_lshlrev_b32_e32 v201, 16, v202
	v_fmac_f32_e32 v201, v144, v136
	v_and_b32_e32 v144, 0xffff0000, v202
	v_fmac_f32_e32 v144, v145, v137
	v_lshlrev_b32_e32 v145, 16, v203
	v_fmac_f32_e32 v145, v146, v138
	v_and_b32_e32 v146, 0xffff0000, v203
	v_fmac_f32_e32 v146, v147, v139
	v_cvt_pk_bf16_f32 v144, v201, v144
	v_cvt_pk_bf16_f32 v145, v145, v146
	v_lshlrev_b32_e32 v146, 16, v204
	v_fmac_f32_e32 v146, v140, v132
	v_and_b32_e32 v140, 0xffff0000, v204
	v_fmac_f32_e32 v140, v141, v133
	v_cvt_pk_bf16_f32 v146, v146, v140
	v_lshlrev_b32_e32 v140, 16, v205
	v_fmac_f32_e32 v140, v142, v134
	v_lshlrev_b32_e32 v142, 16, v172
	v_and_b32_e32 v141, 0xffff0000, v205
	v_fmac_f32_e32 v142, v120, v128
	v_and_b32_e32 v120, 0xffff0000, v172
	v_fmac_f32_e32 v141, v143, v135
	v_fmac_f32_e32 v120, v121, v129
	v_lshlrev_b32_e32 v121, 16, v173
	v_cvt_pk_bf16_f32 v147, v140, v141
	v_lshl_add_u64 v[140:141], s[14:15], 0, v[190:191]
	v_fmac_f32_e32 v121, v122, v130
	v_and_b32_e32 v122, 0xffff0000, v173
	v_lshl_add_u64 v[140:141], v[140:141], 0, v[186:187]
	v_fmac_f32_e32 v122, v123, v131
	flat_store_dwordx4 v[140:141], v[144:147]
	v_cvt_pk_bf16_f32 v120, v142, v120
	v_cvt_pk_bf16_f32 v121, v121, v122
	v_lshlrev_b32_e32 v122, 16, v174
	v_fmac_f32_e32 v122, v116, v124
	v_and_b32_e32 v116, 0xffff0000, v174
	v_fmac_f32_e32 v116, v117, v125
	v_cvt_pk_bf16_f32 v122, v122, v116
	v_lshlrev_b32_e32 v116, 16, v175
	v_fmac_f32_e32 v116, v118, v126
	v_and_b32_e32 v117, 0xffff0000, v175
	v_fmac_f32_e32 v117, v119, v127
	v_cvt_pk_bf16_f32 v123, v116, v117
	v_lshlrev_b32_e32 v116, 16, v168
	v_fmac_f32_e32 v116, v112, v136
	v_and_b32_e32 v112, 0xffff0000, v168
	v_fmac_f32_e32 v112, v113, v137
	v_lshlrev_b32_e32 v113, 16, v169
	v_fmac_f32_e32 v113, v114, v138
	v_and_b32_e32 v114, 0xffff0000, v169
	v_fmac_f32_e32 v114, v115, v139
	flat_store_dwordx4 v[140:141], v[120:123] offset:256
	v_cvt_pk_bf16_f32 v112, v116, v112
	v_cvt_pk_bf16_f32 v113, v113, v114
	v_lshlrev_b32_e32 v114, 16, v170
	v_fmac_f32_e32 v114, v108, v132
	v_and_b32_e32 v108, 0xffff0000, v170
	v_fmac_f32_e32 v108, v109, v133
	v_cvt_pk_bf16_f32 v114, v114, v108
	v_lshlrev_b32_e32 v108, 16, v171
	v_fmac_f32_e32 v108, v110, v134
	v_lshlrev_b32_e32 v110, 16, v164
	v_and_b32_e32 v109, 0xffff0000, v171
	v_fmac_f32_e32 v110, v104, v128
	v_and_b32_e32 v104, 0xffff0000, v164
	v_fmac_f32_e32 v109, v111, v135
	v_fmac_f32_e32 v104, v105, v129
	v_lshlrev_b32_e32 v105, 16, v165
	v_cvt_pk_bf16_f32 v115, v108, v109
	v_lshl_add_u64 v[108:109], s[14:15], 0, v[196:197]
	v_fmac_f32_e32 v105, v106, v130
	v_and_b32_e32 v106, 0xffff0000, v165
	v_lshl_add_u64 v[108:109], v[108:109], 0, v[186:187]
	v_fmac_f32_e32 v106, v107, v131
	flat_store_dwordx4 v[108:109], v[112:115]
	v_cvt_pk_bf16_f32 v104, v110, v104
	v_cvt_pk_bf16_f32 v105, v105, v106
	v_lshlrev_b32_e32 v106, 16, v166
	v_fmac_f32_e32 v106, v96, v124
	v_and_b32_e32 v96, 0xffff0000, v166
	v_fmac_f32_e32 v96, v97, v125
	v_cvt_pk_bf16_f32 v106, v106, v96
	v_lshlrev_b32_e32 v96, 16, v167
	v_and_b32_e32 v97, 0xffff0000, v167
	v_fmac_f32_e32 v96, v98, v126
	v_fmac_f32_e32 v97, v99, v127
	v_cvt_pk_bf16_f32 v107, v96, v97
	v_lshlrev_b32_e32 v96, 16, v160
	v_and_b32_e32 v97, 0xffff0000, v160
	v_fmac_f32_e32 v96, v100, v136
	v_fmac_f32_e32 v97, v101, v137
	flat_store_dwordx4 v[108:109], v[104:107] offset:256
	v_cvt_pk_bf16_f32 v96, v96, v97
	v_lshlrev_b32_e32 v97, 16, v161
	v_and_b32_e32 v98, 0xffff0000, v161
	v_fmac_f32_e32 v97, v102, v138
	v_fmac_f32_e32 v98, v103, v139
	v_cvt_pk_bf16_f32 v97, v97, v98
	v_lshlrev_b32_e32 v98, 16, v162
	v_fmac_f32_e32 v98, v92, v132
	v_and_b32_e32 v92, 0xffff0000, v162
	v_fmac_f32_e32 v92, v93, v133
	v_cvt_pk_bf16_f32 v98, v98, v92
	v_lshlrev_b32_e32 v92, 16, v163
	v_fmac_f32_e32 v92, v94, v134
	v_lshlrev_b32_e32 v94, 16, v152
	v_and_b32_e32 v93, 0xffff0000, v163
	v_fmac_f32_e32 v94, v88, v128
	v_and_b32_e32 v88, 0xffff0000, v152
	v_fmac_f32_e32 v93, v95, v135
	v_fmac_f32_e32 v88, v89, v129
	v_lshlrev_b32_e32 v89, 16, v153
	v_cvt_pk_bf16_f32 v99, v92, v93
	v_lshl_add_u64 v[92:93], s[14:15], 0, v[194:195]
	v_fmac_f32_e32 v89, v90, v130
	v_and_b32_e32 v90, 0xffff0000, v153
	v_lshl_add_u64 v[92:93], v[92:93], 0, v[186:187]
	v_fmac_f32_e32 v90, v91, v131
	flat_store_dwordx4 v[92:93], v[96:99]
	v_cvt_pk_bf16_f32 v88, v94, v88
	v_cvt_pk_bf16_f32 v89, v89, v90
	v_lshlrev_b32_e32 v90, 16, v154
	v_fmac_f32_e32 v90, v80, v124
	v_and_b32_e32 v80, 0xffff0000, v154
	v_fmac_f32_e32 v80, v81, v125
	v_cvt_pk_bf16_f32 v90, v90, v80
	v_lshlrev_b32_e32 v80, 16, v155
	v_and_b32_e32 v81, 0xffff0000, v155
	v_fmac_f32_e32 v80, v82, v126
	v_fmac_f32_e32 v81, v83, v127
	v_cvt_pk_bf16_f32 v91, v80, v81
	v_lshlrev_b32_e32 v80, 16, v156
	v_and_b32_e32 v81, 0xffff0000, v156
	v_fmac_f32_e32 v80, v84, v136
	v_fmac_f32_e32 v81, v85, v137
	flat_store_dwordx4 v[92:93], v[88:91] offset:256
	v_cvt_pk_bf16_f32 v80, v80, v81
	v_lshlrev_b32_e32 v81, 16, v157
	v_and_b32_e32 v82, 0xffff0000, v157
	v_fmac_f32_e32 v81, v86, v138
	v_fmac_f32_e32 v82, v87, v139
	v_cvt_pk_bf16_f32 v81, v81, v82
	v_lshlrev_b32_e32 v82, 16, v158
	v_fmac_f32_e32 v82, v76, v132
	v_and_b32_e32 v76, 0xffff0000, v158
	v_fmac_f32_e32 v76, v77, v133
	v_cvt_pk_bf16_f32 v82, v82, v76
	v_lshlrev_b32_e32 v76, 16, v159
	v_fmac_f32_e32 v76, v78, v134
	v_lshlrev_b32_e32 v78, 16, v148
	v_and_b32_e32 v77, 0xffff0000, v159
	v_fmac_f32_e32 v78, v72, v128
	v_and_b32_e32 v72, 0xffff0000, v148
	v_fmac_f32_e32 v77, v79, v135
	v_fmac_f32_e32 v72, v73, v129
	v_lshlrev_b32_e32 v73, 16, v149
	v_cvt_pk_bf16_f32 v83, v76, v77
	v_lshl_add_u64 v[76:77], s[14:15], 0, v[192:193]
	v_fmac_f32_e32 v73, v74, v130
	v_and_b32_e32 v74, 0xffff0000, v149
; __device__ __forceinline__ unsigned cvt_pk_bf16(float lo, float hi) { unsigned r; asm volatile("v_cvt_pk_bf16_f32 %0, %1, %2" : "=v"(r) : "v"(lo), "v"(hi)); return r; }
;     __device__ __forceinline__ void operator()(const f32x4 (&acc)[2][2][4][2], const Unit& u, int wr, int wc, int fr, int fq) const {
;     ...
;                 for (int m = 0; m < 4; ++m) { const size_t off = (size_t)(row0 + ai * HALF + m * 16) * ldc + col0;
; #pragma unroll
;                     for (int bj = 0; bj < 2; ++bj) bs[m][bj] = *(const u32x4*)(bp + off + bj * HALF); }
;     ...
;                 for (int m = 0; m < 4; ++m) { const size_t off = (size_t)(row0 + ai * HALF + m * 16) * ldc + col0;
; #pragma unroll
;                     for (int bj = 0; bj < 2; ++bj) { const u32x4 r = bs[m][bj]; const f32x4 a0 = acc[ai][bj][m][0], a1 = acc[ai][bj][m][1];
;                         u32x4 w;
;                         w.x = cvt_pk_bf16(__builtin_bit_cast(float, r.x << 16) + gv[bj][0][0] * a0[0], __builtin_bit_cast(float, r.x & 0xffff0000u) + gv[bj][0][1] * a0[1]);
;                         w.y = cvt_pk_bf16(__builtin_bit_cast(float, r.y << 16) + gv[bj][0][2] * a0[2], __builtin_bit_cast(float, r.y & 0xffff0000u) + gv[bj][0][3] * a0[3]);
;                         w.z = cvt_pk_bf16(__builtin_bit_cast(float, r.z << 16) + gv[bj][1][0] * a1[0], __builtin_bit_cast(float, r.z & 0xffff0000u) + gv[bj][1][1] * a1[1]);
;                         w.w = cvt_pk_bf16(__builtin_bit_cast(float, r.w << 16) + gv[bj][1][2] * a1[2], __builtin_bit_cast(float, r.w & 0xffff0000u) + gv[bj][1][3] * a1[3]);
;                         *(u32x4*)(out + off + bj * HALF) = w; } }
	v_lshl_add_u64 v[76:77], v[76:77], 0, v[186:187]
	v_fmac_f32_e32 v74, v75, v131
	flat_store_dwordx4 v[76:77], v[80:83]
	v_cvt_pk_bf16_f32 v72, v78, v72
	v_cvt_pk_bf16_f32 v73, v73, v74
	v_lshlrev_b32_e32 v74, 16, v150
	v_fmac_f32_e32 v74, v68, v124
	v_and_b32_e32 v68, 0xffff0000, v150
	v_fmac_f32_e32 v68, v69, v125
	v_cvt_pk_bf16_f32 v74, v74, v68
	v_lshlrev_b32_e32 v68, 16, v151
	v_and_b32_e32 v69, 0xffff0000, v151
	v_fmac_f32_e32 v68, v70, v126
	v_fmac_f32_e32 v69, v71, v127
	v_cvt_pk_bf16_f32 v75, v68, v69
	flat_store_dwordx4 v[76:77], v[72:75] offset:256
	v_lshl_add_u64 v[100:101], v[190:191], 0, s[20:21]
	v_lshl_add_u64 v[68:69], v[188:189], 0, v[100:101]
	flat_load_dwordx4 v[72:75], v[68:69]
	flat_load_dwordx4 v[76:79], v[68:69] offset:256
	s_mov_b64 s[20:21], 0x90000
	v_lshl_add_u64 v[102:103], v[190:191], 0, s[20:21]
	v_lshl_add_u64 v[68:69], v[188:189], 0, v[102:103]
	flat_load_dwordx4 v[80:83], v[68:69]
	flat_load_dwordx4 v[84:87], v[68:69] offset:256
	s_mov_b64 s[20:21], 0xa0000
	v_lshl_add_u64 v[104:105], v[190:191], 0, s[20:21]
	v_lshl_add_u64 v[68:69], v[188:189], 0, v[104:105]
	flat_load_dwordx4 v[88:91], v[68:69]
	flat_load_dwordx4 v[92:95], v[68:69] offset:256
	s_mov_b64 s[20:21], 0xb0000
	v_lshl_add_u64 v[106:107], v[190:191], 0, s[20:21]
	v_lshl_add_u64 v[68:69], v[188:189], 0, v[106:107]
	flat_load_dwordx4 v[96:99], v[68:69]
	s_nop 0
	flat_load_dwordx4 v[68:71], v[68:69] offset:256
	s_mov_b64 s[20:21], s[16:17]
	s_waitcnt vmcnt(0) lgkmcnt(0)
; __device__ __forceinline__ unsigned cvt_pk_bf16(float lo, float hi) { unsigned r; asm volatile("v_cvt_pk_bf16_f32 %0, %1, %2" : "=v"(r) : "v"(lo), "v"(hi)); return r; }
; #define PG8_WAIT_V(n) asm volatile("s_waitcnt vmcnt(" #n ")" ::: "memory")
; #define PG8_BAR __builtin_amdgcn_s_barrier()
;     __device__ __forceinline__ void operator()(const f32x4 (&acc)[2][2][4][2], const Unit& u, int wr, int wc, int fr, int fq) const {
;     ...
;                 for (int m = 0; m < 4; ++m) { const size_t off = (size_t)(row0 + ai * HALF + m * 16) * ldc + col0;
; #pragma unroll
;                     for (int bj = 0; bj < 2; ++bj) { const u32x4 r = bs[m][bj]; const f32x4 a0 = acc[ai][bj][m][0], a1 = acc[ai][bj][m][1];
;                         u32x4 w;
;                         w.x = cvt_pk_bf16(__builtin_bit_cast(float, r.x << 16) + gv[bj][0][0] * a0[0], __builtin_bit_cast(float, r.x & 0xffff0000u) + gv[bj][0][1] * a0[1]);
;                         w.y = cvt_pk_bf16(__builtin_bit_cast(float, r.y << 16) + gv[bj][0][2] * a0[2], __builtin_bit_cast(float, r.y & 0xffff0000u) + gv[bj][0][3] * a0[3]);
;                         w.z = cvt_pk_bf16(__builtin_bit_cast(float, r.z << 16) + gv[bj][1][0] * a1[0], __builtin_bit_cast(float, r.z & 0xffff0000u) + gv[bj][1][1] * a1[1]);
;                         w.w = cvt_pk_bf16(__builtin_bit_cast(float, r.w << 16) + gv[bj][1][2] * a1[2], __builtin_bit_cast(float, r.w & 0xffff0000u) + gv[bj][1][3] * a1[3]);
;                         *(u32x4*)(out + off + bj * HALF) = w; } }
;                 asm volatile("" ::: "memory"); }
; template <class Epi, class Sched, bool ALIGN_EPI = false, bool SP2 = false>
; __device__ __forceinline__ void gemm_phase(PG8_LAS unsigned char* lds, const Gemm g, const Sched& S, const Epi& E) {
;     ...
;         if (!has_next) break;
; #pragma unroll
;         for (int a = 0; a < 2; ++a)
; #pragma unroll
;             for (int b = 0; b < 2; ++b)
; #pragma unroll
;                 for (int m = 0; m < 4; ++m)
; #pragma unroll
;                     for (int n = 0; n < 2; ++n) acc[a][b][m][n] = (f32x4){0.f, 0.f, 0.f, 0.f};
;         cur = nxt; cA = nA; cB = nB; ++ui;
;         if constexpr (ALIGN_EPI) { if (wr == 1) PG8_BAR; }
;     }
;     PG8_WAIT_V(0);
;     if constexpr (!ALIGN_EPI) { if (wr == 0) PG8_BAR; }
;     PG8_BAR;
	v_lshlrev_b32_e32 v108, 16, v72
	v_fmac_f32_e32 v108, v64, v136
	v_and_b32_e32 v64, 0xffff0000, v72
	v_fmac_f32_e32 v64, v65, v137
	v_lshlrev_b32_e32 v65, 16, v73
	v_fmac_f32_e32 v65, v66, v138
	v_and_b32_e32 v66, 0xffff0000, v73
	v_fmac_f32_e32 v66, v67, v139
	v_cvt_pk_bf16_f32 v64, v108, v64
	v_cvt_pk_bf16_f32 v65, v65, v66
	v_lshlrev_b32_e32 v66, 16, v74
	v_fmac_f32_e32 v66, v60, v132
	v_and_b32_e32 v60, 0xffff0000, v74
	v_fmac_f32_e32 v60, v61, v133
	v_cvt_pk_bf16_f32 v66, v66, v60
	v_lshlrev_b32_e32 v60, 16, v75
	v_fmac_f32_e32 v60, v62, v134
	v_lshlrev_b32_e32 v62, 16, v76
	v_and_b32_e32 v61, 0xffff0000, v75
	v_fmac_f32_e32 v62, v56, v128
	v_and_b32_e32 v56, 0xffff0000, v76
	v_fmac_f32_e32 v61, v63, v135
	v_fmac_f32_e32 v56, v57, v129
	v_lshlrev_b32_e32 v57, 16, v77
	v_cvt_pk_bf16_f32 v67, v60, v61
	v_lshl_add_u64 v[60:61], s[14:15], 0, v[100:101]
	v_fmac_f32_e32 v57, v58, v130
	v_and_b32_e32 v58, 0xffff0000, v77
	v_lshl_add_u64 v[60:61], v[60:61], 0, v[186:187]
	v_fmac_f32_e32 v58, v59, v131
	flat_store_dwordx4 v[60:61], v[64:67]
	v_cvt_pk_bf16_f32 v56, v62, v56
	v_cvt_pk_bf16_f32 v57, v57, v58
	v_lshlrev_b32_e32 v58, 16, v78
	v_fmac_f32_e32 v58, v48, v124
	v_and_b32_e32 v48, 0xffff0000, v78
	v_fmac_f32_e32 v48, v49, v125
	v_cvt_pk_bf16_f32 v58, v58, v48
	v_lshlrev_b32_e32 v48, 16, v79
	v_and_b32_e32 v49, 0xffff0000, v79
	v_fmac_f32_e32 v48, v50, v126
	v_fmac_f32_e32 v49, v51, v127
	v_cvt_pk_bf16_f32 v59, v48, v49
	v_lshlrev_b32_e32 v48, 16, v80
	v_and_b32_e32 v49, 0xffff0000, v80
	v_fmac_f32_e32 v48, v52, v136
	v_fmac_f32_e32 v49, v53, v137
	flat_store_dwordx4 v[60:61], v[56:59] offset:256
	v_cvt_pk_bf16_f32 v48, v48, v49
	v_lshlrev_b32_e32 v49, 16, v81
	v_and_b32_e32 v50, 0xffff0000, v81
	v_fmac_f32_e32 v49, v54, v138
	v_fmac_f32_e32 v50, v55, v139
	v_cvt_pk_bf16_f32 v49, v49, v50
	v_lshlrev_b32_e32 v50, 16, v82
	v_fmac_f32_e32 v50, v44, v132
	v_and_b32_e32 v44, 0xffff0000, v82
	v_fmac_f32_e32 v44, v45, v133
	v_cvt_pk_bf16_f32 v50, v50, v44
	v_lshlrev_b32_e32 v44, 16, v83
	v_fmac_f32_e32 v44, v46, v134
	v_lshlrev_b32_e32 v46, 16, v84
	v_and_b32_e32 v45, 0xffff0000, v83
	v_fmac_f32_e32 v46, v40, v128
	v_and_b32_e32 v40, 0xffff0000, v84
	v_fmac_f32_e32 v45, v47, v135
	v_fmac_f32_e32 v40, v41, v129
	v_lshlrev_b32_e32 v41, 16, v85
	v_cvt_pk_bf16_f32 v51, v44, v45
	v_lshl_add_u64 v[44:45], s[14:15], 0, v[102:103]
	v_fmac_f32_e32 v41, v42, v130
	v_and_b32_e32 v42, 0xffff0000, v85
	v_lshl_add_u64 v[44:45], v[44:45], 0, v[186:187]
	v_fmac_f32_e32 v42, v43, v131
	flat_store_dwordx4 v[44:45], v[48:51]
	v_cvt_pk_bf16_f32 v40, v46, v40
	v_cvt_pk_bf16_f32 v41, v41, v42
	v_lshlrev_b32_e32 v42, 16, v86
	v_fmac_f32_e32 v42, v32, v124
	v_and_b32_e32 v32, 0xffff0000, v86
	v_fmac_f32_e32 v32, v33, v125
	v_cvt_pk_bf16_f32 v42, v42, v32
	v_lshlrev_b32_e32 v32, 16, v87
	v_and_b32_e32 v33, 0xffff0000, v87
	v_fmac_f32_e32 v32, v34, v126
	v_fmac_f32_e32 v33, v35, v127
	v_cvt_pk_bf16_f32 v43, v32, v33
	v_lshlrev_b32_e32 v32, 16, v88
	v_and_b32_e32 v33, 0xffff0000, v88
	v_fmac_f32_e32 v32, v36, v136
	v_fmac_f32_e32 v33, v37, v137
	flat_store_dwordx4 v[44:45], v[40:43] offset:256
	v_cvt_pk_bf16_f32 v32, v32, v33
	v_lshlrev_b32_e32 v33, 16, v89
	v_and_b32_e32 v34, 0xffff0000, v89
	v_fmac_f32_e32 v33, v38, v138
	v_fmac_f32_e32 v34, v39, v139
	v_cvt_pk_bf16_f32 v33, v33, v34
	v_lshlrev_b32_e32 v34, 16, v90
	v_fmac_f32_e32 v34, v28, v132
	v_and_b32_e32 v28, 0xffff0000, v90
	v_fmac_f32_e32 v28, v29, v133
	v_cvt_pk_bf16_f32 v34, v34, v28
	v_lshlrev_b32_e32 v28, 16, v91
	v_fmac_f32_e32 v28, v30, v134
	v_lshlrev_b32_e32 v30, 16, v92
	v_and_b32_e32 v29, 0xffff0000, v91
	v_fmac_f32_e32 v30, v24, v128
	v_and_b32_e32 v24, 0xffff0000, v92
	v_fmac_f32_e32 v29, v31, v135
	v_fmac_f32_e32 v24, v25, v129
	v_lshlrev_b32_e32 v25, 16, v93
	v_cvt_pk_bf16_f32 v35, v28, v29
	v_lshl_add_u64 v[28:29], s[14:15], 0, v[104:105]
	v_fmac_f32_e32 v25, v26, v130
	v_and_b32_e32 v26, 0xffff0000, v93
	v_lshl_add_u64 v[28:29], v[28:29], 0, v[186:187]
	v_fmac_f32_e32 v26, v27, v131
	flat_store_dwordx4 v[28:29], v[32:35]
	v_cvt_pk_bf16_f32 v24, v30, v24
	v_cvt_pk_bf16_f32 v25, v25, v26
	v_lshlrev_b32_e32 v26, 16, v94
	v_fmac_f32_e32 v26, v16, v124
	v_and_b32_e32 v16, 0xffff0000, v94
	v_fmac_f32_e32 v16, v17, v125
	v_cvt_pk_bf16_f32 v26, v26, v16
	v_lshlrev_b32_e32 v16, 16, v95
	v_and_b32_e32 v17, 0xffff0000, v95
	v_fmac_f32_e32 v16, v18, v126
	v_fmac_f32_e32 v17, v19, v127
	v_cvt_pk_bf16_f32 v27, v16, v17
	v_lshlrev_b32_e32 v16, 16, v96
	v_and_b32_e32 v17, 0xffff0000, v96
	v_fmac_f32_e32 v16, v20, v136
	v_fmac_f32_e32 v17, v21, v137
	flat_store_dwordx4 v[28:29], v[24:27] offset:256
	v_cvt_pk_bf16_f32 v16, v16, v17
	v_lshlrev_b32_e32 v17, 16, v97
	v_and_b32_e32 v18, 0xffff0000, v97
	v_fmac_f32_e32 v17, v22, v138
	v_fmac_f32_e32 v18, v23, v139
	v_cvt_pk_bf16_f32 v17, v17, v18
	v_lshlrev_b32_e32 v18, 16, v98
	v_fmac_f32_e32 v18, v12, v132
	v_and_b32_e32 v12, 0xffff0000, v98
	v_fmac_f32_e32 v12, v13, v133
	v_cvt_pk_bf16_f32 v18, v18, v12
	v_lshlrev_b32_e32 v12, 16, v99
	v_fmac_f32_e32 v12, v14, v134
	v_lshlrev_b32_e32 v14, 16, v68
	v_and_b32_e32 v13, 0xffff0000, v99
	v_fmac_f32_e32 v14, v8, v128
	v_and_b32_e32 v8, 0xffff0000, v68
	v_fmac_f32_e32 v13, v15, v135
	v_fmac_f32_e32 v8, v9, v129
	v_lshlrev_b32_e32 v9, 16, v69
	v_cvt_pk_bf16_f32 v19, v12, v13
	v_lshl_add_u64 v[12:13], s[14:15], 0, v[106:107]
	v_fmac_f32_e32 v9, v10, v130
	v_and_b32_e32 v10, 0xffff0000, v69
	v_lshl_add_u64 v[12:13], v[12:13], 0, v[186:187]
	v_fmac_f32_e32 v10, v11, v131
	flat_store_dwordx4 v[12:13], v[16:19]
	v_cvt_pk_bf16_f32 v8, v14, v8
	v_cvt_pk_bf16_f32 v9, v9, v10
	v_lshlrev_b32_e32 v10, 16, v70
	v_fmac_f32_e32 v10, v4, v124
	v_and_b32_e32 v4, 0xffff0000, v70
	v_fmac_f32_e32 v4, v5, v125
	v_cvt_pk_bf16_f32 v10, v10, v4
	v_lshlrev_b32_e32 v4, 16, v71
	v_and_b32_e32 v5, 0xffff0000, v71
	v_fmac_f32_e32 v4, v6, v126
	v_fmac_f32_e32 v5, v7, v127
	v_cvt_pk_bf16_f32 v11, v4, v5
	flat_store_dwordx4 v[12:13], v[8:11] offset:256
	s_cbranch_vccz .LBB0_2227
	s_waitcnt vmcnt(0)
	s_cmpk_gt_u32 s7, 0xff
	s_cbranch_scc1 .LBB0_2242
	s_barrier
